# v35 + merged 16-byte z stores in the w_in epilogue
# baseline (speedup 1.0000x reference)
.LBB0_412:
	ds_read_b128 v[128:131], v170
	ds_read_b128 v[132:135], v170 offset:1024
	ds_read_b128 v[164:167], v170 offset:2048
	ds_read_b128 v[176:179], v170 offset:3072
	s_add_u32 s8, s6, 0xfffc0080
	s_addc_u32 s9, s7, -1
	s_cmp_eq_u32 s38, 12
	s_cselect_b32 s11, s25, s9
	s_cselect_b32 s10, s31, s8
	s_cselect_b32 s9, s23, s36
	s_cselect_b32 s8, s34, s35
	v_lshl_add_u64 v[168:169], s[6:7], 0, v[158:159]
	s_add_i32 m0, s49, 0xc000
	ds_read_b128 v[180:183], v171
	ds_read_b128 v[184:187], v171 offset:1024
	ds_read_b128 v[188:191], v171 offset:2048
	ds_read_b128 v[192:195], v171 offset:3072
	ds_read_b128 v[196:199], v171 offset:4096
	ds_read_b128 v[200:203], v171 offset:5120
	ds_read_b128 v[204:207], v171 offset:6144
	ds_read_b128 v[208:211], v171 offset:7168
	global_load_lds_dwordx4 v[168:169], off
	v_lshl_add_u64 v[168:169], s[6:7], 0, v[156:157]
	s_add_i32 m0, s49, 0xe000
	s_nop 0
	global_load_lds_dwordx4 v[168:169], off
	s_waitcnt lgkmcnt(8)
	s_waitcnt vmcnt(10)
	s_barrier
	s_waitcnt lgkmcnt(0)
	s_setprio 1
	s_waitcnt lgkmcnt(0)
	v_mfma_f32_16x16x32_bf16 v[124:127], v[128:131], v[180:183], v[124:127]
	v_mfma_f32_16x16x32_bf16 v[120:123], v[164:167], v[180:183], v[120:123]
	v_mfma_f32_16x16x32_bf16 v[108:111], v[128:131], v[188:191], v[108:111]
	v_mfma_f32_16x16x32_bf16 v[104:107], v[164:167], v[188:191], v[104:107]
	v_mfma_f32_16x16x32_bf16 v[92:95], v[128:131], v[196:199], v[92:95]
	v_mfma_f32_16x16x32_bf16 v[88:91], v[164:167], v[196:199], v[88:91]
	v_mfma_f32_16x16x32_bf16 v[76:79], v[128:131], v[204:207], v[76:79]
	v_mfma_f32_16x16x32_bf16 v[72:75], v[164:167], v[204:207], v[72:75]
	v_mfma_f32_16x16x32_bf16 v[124:127], v[132:135], v[184:187], v[124:127]
	v_mfma_f32_16x16x32_bf16 v[120:123], v[176:179], v[184:187], v[120:123]
	v_mfma_f32_16x16x32_bf16 v[108:111], v[132:135], v[192:195], v[108:111]
	v_mfma_f32_16x16x32_bf16 v[104:107], v[176:179], v[192:195], v[104:107]
	v_mfma_f32_16x16x32_bf16 v[92:95], v[132:135], v[200:203], v[92:95]
	v_mfma_f32_16x16x32_bf16 v[88:91], v[176:179], v[200:203], v[88:91]
	v_mfma_f32_16x16x32_bf16 v[76:79], v[132:135], v[208:211], v[76:79]
	v_mfma_f32_16x16x32_bf16 v[72:75], v[176:179], v[208:211], v[72:75]
	s_setprio 0
	s_barrier
	s_add_i32 s39, s58, s48
	v_lshl_add_u64 v[168:169], s[8:9], 0, v[138:139]
	s_mov_b32 m0, s39
	ds_read_b128 v[212:215], v172
	ds_read_b128 v[216:219], v172 offset:1024
	ds_read_b128 v[220:223], v172 offset:2048
	ds_read_b128 v[224:227], v172 offset:3072
	global_load_lds_dwordx4 v[168:169], off
	v_lshl_add_u64 v[228:229], s[8:9], 0, v[136:137]
	s_add_i32 m0, s39, 0x2000
	s_nop 0
	global_load_lds_dwordx4 v[228:229], off
	s_waitcnt vmcnt(10)
	s_barrier
	s_waitcnt lgkmcnt(0)
	s_setprio 1
	s_waitcnt lgkmcnt(0)
	v_mfma_f32_16x16x32_bf16 v[116:119], v[212:215], v[180:183], v[116:119]
	v_mfma_f32_16x16x32_bf16 v[112:115], v[220:223], v[180:183], v[112:115]
	v_mfma_f32_16x16x32_bf16 v[100:103], v[212:215], v[188:191], v[100:103]
	v_mfma_f32_16x16x32_bf16 v[96:99], v[220:223], v[188:191], v[96:99]
	v_mfma_f32_16x16x32_bf16 v[84:87], v[212:215], v[196:199], v[84:87]
	v_mfma_f32_16x16x32_bf16 v[80:83], v[220:223], v[196:199], v[80:83]
	v_mfma_f32_16x16x32_bf16 v[68:71], v[212:215], v[204:207], v[68:71]
	v_mfma_f32_16x16x32_bf16 v[64:67], v[220:223], v[204:207], v[64:67]
	v_mfma_f32_16x16x32_bf16 v[116:119], v[216:219], v[184:187], v[116:119]
	v_mfma_f32_16x16x32_bf16 v[112:115], v[224:227], v[184:187], v[112:115]
	v_mfma_f32_16x16x32_bf16 v[100:103], v[216:219], v[192:195], v[100:103]
	v_mfma_f32_16x16x32_bf16 v[96:99], v[224:227], v[192:195], v[96:99]
	v_mfma_f32_16x16x32_bf16 v[84:87], v[216:219], v[200:203], v[84:87]
	v_mfma_f32_16x16x32_bf16 v[80:83], v[224:227], v[200:203], v[80:83]
	v_mfma_f32_16x16x32_bf16 v[68:71], v[216:219], v[208:211], v[68:71]
	v_mfma_f32_16x16x32_bf16 v[64:67], v[224:227], v[208:211], v[64:67]
	s_setprio 0
	s_mov_b32 m0, s49
	v_lshl_add_u64 v[230:231], s[10:11], 0, v[138:139]
	s_barrier
	ds_read_b128 v[180:183], v171 offset:16384
	ds_read_b128 v[184:187], v171 offset:17408
	ds_read_b128 v[188:191], v171 offset:18432
	ds_read_b128 v[192:195], v171 offset:19456
	ds_read_b128 v[196:199], v171 offset:20480
	ds_read_b128 v[200:203], v171 offset:21504
	ds_read_b128 v[204:207], v171 offset:22528
	ds_read_b128 v[208:211], v171 offset:23552
	global_load_lds_dwordx4 v[230:231], off
	v_lshl_add_u64 v[232:233], s[10:11], 0, v[136:137]
	s_mov_b32 m0, s50
	s_nop 0
	global_load_lds_dwordx4 v[232:233], off
	s_barrier
	s_waitcnt lgkmcnt(0)
	s_setprio 1
	s_waitcnt lgkmcnt(0)
	v_mfma_f32_16x16x32_bf16 v[60:63], v[128:131], v[180:183], v[60:63]
	v_mfma_f32_16x16x32_bf16 v[56:59], v[164:167], v[180:183], v[56:59]
	v_mfma_f32_16x16x32_bf16 v[44:47], v[128:131], v[188:191], v[44:47]
	v_mfma_f32_16x16x32_bf16 v[40:43], v[164:167], v[188:191], v[40:43]
	v_mfma_f32_16x16x32_bf16 v[28:31], v[128:131], v[196:199], v[28:31]
	v_mfma_f32_16x16x32_bf16 v[24:27], v[164:167], v[196:199], v[24:27]
	v_mfma_f32_16x16x32_bf16 v[12:15], v[128:131], v[204:207], v[12:15]
	v_mfma_f32_16x16x32_bf16 v[8:11], v[164:167], v[204:207], v[8:11]
	v_mfma_f32_16x16x32_bf16 v[60:63], v[132:135], v[184:187], v[60:63]
	v_mfma_f32_16x16x32_bf16 v[56:59], v[176:179], v[184:187], v[56:59]
	v_mfma_f32_16x16x32_bf16 v[44:47], v[132:135], v[192:195], v[44:47]
	v_mfma_f32_16x16x32_bf16 v[40:43], v[176:179], v[192:195], v[40:43]
	v_mfma_f32_16x16x32_bf16 v[28:31], v[132:135], v[200:203], v[28:31]
	v_mfma_f32_16x16x32_bf16 v[24:27], v[176:179], v[200:203], v[24:27]
	v_mfma_f32_16x16x32_bf16 v[12:15], v[132:135], v[208:211], v[12:15]
	v_mfma_f32_16x16x32_bf16 v[8:11], v[176:179], v[208:211], v[8:11]
	s_setprio 0
	s_barrier
	s_add_u32 s40, s8, 0x40000
	s_addc_u32 s41, s9, 0
	s_add_i32 s39, s59, s48
	v_lshl_add_u64 v[128:129], s[40:41], 0, v[138:139]
	s_mov_b32 m0, s39
	s_nop 0
	global_load_lds_dwordx4 v[128:129], off
	v_lshl_add_u64 v[128:129], s[40:41], 0, v[136:137]
	s_add_i32 m0, s39, 0x2000
	s_nop 0
	global_load_lds_dwordx4 v[128:129], off
	s_waitcnt vmcnt(10)
	s_barrier
	s_setprio 1
	v_mfma_f32_16x16x32_bf16 v[52:55], v[212:215], v[180:183], v[52:55]
	v_mfma_f32_16x16x32_bf16 v[48:51], v[220:223], v[180:183], v[48:51]
	v_mfma_f32_16x16x32_bf16 v[36:39], v[212:215], v[188:191], v[36:39]
	v_mfma_f32_16x16x32_bf16 v[32:35], v[220:223], v[188:191], v[32:35]
	v_mfma_f32_16x16x32_bf16 v[20:23], v[212:215], v[196:199], v[20:23]
	v_mfma_f32_16x16x32_bf16 v[16:19], v[220:223], v[196:199], v[16:19]
	v_mfma_f32_16x16x32_bf16 v[4:7], v[212:215], v[204:207], v[4:7]
	v_mfma_f32_16x16x32_bf16 v[0:3], v[220:223], v[204:207], v[0:3]
	v_mfma_f32_16x16x32_bf16 v[52:55], v[216:219], v[184:187], v[52:55]
	v_mfma_f32_16x16x32_bf16 v[48:51], v[224:227], v[184:187], v[48:51]
	v_mfma_f32_16x16x32_bf16 v[36:39], v[216:219], v[192:195], v[36:39]
	v_mfma_f32_16x16x32_bf16 v[32:35], v[224:227], v[192:195], v[32:35]
	v_mfma_f32_16x16x32_bf16 v[20:23], v[216:219], v[200:203], v[20:23]
	v_mfma_f32_16x16x32_bf16 v[16:19], v[224:227], v[200:203], v[16:19]
	v_mfma_f32_16x16x32_bf16 v[4:7], v[216:219], v[208:211], v[4:7]
	v_mfma_f32_16x16x32_bf16 v[0:3], v[224:227], v[208:211], v[0:3]
	s_setprio 0
	s_add_i32 s39, 0, 0x18000
	v_add_u32_e32 v176, s39, v149
	s_barrier
	ds_read_b128 v[128:131], v176
	ds_read_b128 v[132:135], v176 offset:1024
	ds_read_b128 v[164:167], v176 offset:2048
	ds_read_b128 v[176:179], v176 offset:3072
	s_add_u32 s10, s10, 0x40000
	s_addc_u32 s11, s11, 0
	s_mov_b32 m0, s51
	v_lshl_add_u64 v[212:213], s[10:11], 0, v[138:139]
	ds_read_b128 v[180:183], v171 offset:32768
	ds_read_b128 v[184:187], v171 offset:33792
	ds_read_b128 v[188:191], v171 offset:34816
	ds_read_b128 v[192:195], v171 offset:35840
	ds_read_b128 v[196:199], v171 offset:36864
	ds_read_b128 v[200:203], v171 offset:37888
	ds_read_b128 v[204:207], v171 offset:38912
	ds_read_b128 v[208:211], v171 offset:39936
	global_load_lds_dwordx4 v[212:213], off
	v_lshl_add_u64 v[212:213], s[10:11], 0, v[136:137]
	s_mov_b32 m0, s52
	s_nop 0
	global_load_lds_dwordx4 v[212:213], off
	s_waitcnt lgkmcnt(8)
	s_waitcnt vmcnt(10)
	s_barrier
	s_waitcnt lgkmcnt(0)
	s_setprio 1
	s_waitcnt lgkmcnt(0)
	v_mfma_f32_16x16x32_bf16 v[124:127], v[128:131], v[180:183], v[124:127]
	v_mfma_f32_16x16x32_bf16 v[120:123], v[164:167], v[180:183], v[120:123]
	v_mfma_f32_16x16x32_bf16 v[108:111], v[128:131], v[188:191], v[108:111]
	v_mfma_f32_16x16x32_bf16 v[104:107], v[164:167], v[188:191], v[104:107]
	v_mfma_f32_16x16x32_bf16 v[92:95], v[128:131], v[196:199], v[92:95]
	v_mfma_f32_16x16x32_bf16 v[88:91], v[164:167], v[196:199], v[88:91]
	v_mfma_f32_16x16x32_bf16 v[76:79], v[128:131], v[204:207], v[76:79]
	v_mfma_f32_16x16x32_bf16 v[72:75], v[164:167], v[204:207], v[72:75]
	v_mfma_f32_16x16x32_bf16 v[124:127], v[132:135], v[184:187], v[124:127]
	v_mfma_f32_16x16x32_bf16 v[120:123], v[176:179], v[184:187], v[120:123]
	v_mfma_f32_16x16x32_bf16 v[108:111], v[132:135], v[192:195], v[108:111]
	v_mfma_f32_16x16x32_bf16 v[104:107], v[176:179], v[192:195], v[104:107]
	v_mfma_f32_16x16x32_bf16 v[92:95], v[132:135], v[200:203], v[92:95]
	v_mfma_f32_16x16x32_bf16 v[88:91], v[176:179], v[200:203], v[88:91]
	v_mfma_f32_16x16x32_bf16 v[76:79], v[132:135], v[208:211], v[76:79]
	v_mfma_f32_16x16x32_bf16 v[72:75], v[176:179], v[208:211], v[72:75]
	s_setprio 0
	s_barrier
	s_add_i32 s10, 0, 0x1c000
	s_add_i32 s11, s39, s48
	v_add_u32_e32 v224, s10, v149
	v_lshl_add_u64 v[168:169], v[168:169], 0, s[16:17]
	s_mov_b32 m0, s11
	ds_read_b128 v[212:215], v224
	ds_read_b128 v[216:219], v224 offset:1024
	ds_read_b128 v[220:223], v224 offset:2048
	ds_read_b128 v[224:227], v224 offset:3072
	global_load_lds_dwordx4 v[168:169], off
	v_lshl_add_u64 v[168:169], v[228:229], 0, s[16:17]
	s_add_i32 m0, s11, 0x2000
	s_nop 0
	global_load_lds_dwordx4 v[168:169], off
	s_waitcnt vmcnt(10)
	s_barrier
	s_waitcnt lgkmcnt(0)
	s_setprio 1
	s_waitcnt lgkmcnt(0)
	v_mfma_f32_16x16x32_bf16 v[116:119], v[212:215], v[180:183], v[116:119]
	v_mfma_f32_16x16x32_bf16 v[112:115], v[220:223], v[180:183], v[112:115]
	v_mfma_f32_16x16x32_bf16 v[100:103], v[212:215], v[188:191], v[100:103]
	v_mfma_f32_16x16x32_bf16 v[96:99], v[220:223], v[188:191], v[96:99]
	v_mfma_f32_16x16x32_bf16 v[84:87], v[212:215], v[196:199], v[84:87]
	v_mfma_f32_16x16x32_bf16 v[80:83], v[220:223], v[196:199], v[80:83]
	v_mfma_f32_16x16x32_bf16 v[68:71], v[212:215], v[204:207], v[68:71]
	v_mfma_f32_16x16x32_bf16 v[64:67], v[220:223], v[204:207], v[64:67]
	v_mfma_f32_16x16x32_bf16 v[116:119], v[216:219], v[184:187], v[116:119]
	v_mfma_f32_16x16x32_bf16 v[112:115], v[224:227], v[184:187], v[112:115]
	v_mfma_f32_16x16x32_bf16 v[100:103], v[216:219], v[192:195], v[100:103]
	v_mfma_f32_16x16x32_bf16 v[96:99], v[224:227], v[192:195], v[96:99]
	v_mfma_f32_16x16x32_bf16 v[84:87], v[216:219], v[200:203], v[84:87]
	v_mfma_f32_16x16x32_bf16 v[80:83], v[224:227], v[200:203], v[80:83]
	v_mfma_f32_16x16x32_bf16 v[68:71], v[216:219], v[208:211], v[68:71]
	v_mfma_f32_16x16x32_bf16 v[64:67], v[224:227], v[208:211], v[64:67]
	s_setprio 0
	s_mov_b32 m0, s56
	v_lshl_add_u64 v[168:169], v[230:231], 0, s[16:17]
	s_barrier
	ds_read_b128 v[180:183], v171 offset:49152
	ds_read_b128 v[184:187], v171 offset:50176
	ds_read_b128 v[188:191], v171 offset:51200
	ds_read_b128 v[192:195], v171 offset:52224
	ds_read_b128 v[196:199], v171 offset:53248
	ds_read_b128 v[200:203], v171 offset:54272
	ds_read_b128 v[204:207], v171 offset:55296
	ds_read_b128 v[208:211], v171 offset:56320
	global_load_lds_dwordx4 v[168:169], off
	v_lshl_add_u64 v[168:169], v[232:233], 0, s[16:17]
	s_mov_b32 m0, s57
	s_nop 0
	global_load_lds_dwordx4 v[168:169], off
	s_barrier
	s_waitcnt lgkmcnt(0)
	s_setprio 1
	s_waitcnt lgkmcnt(0)
	v_mfma_f32_16x16x32_bf16 v[60:63], v[128:131], v[180:183], v[60:63]
	v_mfma_f32_16x16x32_bf16 v[56:59], v[164:167], v[180:183], v[56:59]
	v_mfma_f32_16x16x32_bf16 v[44:47], v[128:131], v[188:191], v[44:47]
	v_mfma_f32_16x16x32_bf16 v[40:43], v[164:167], v[188:191], v[40:43]
	v_mfma_f32_16x16x32_bf16 v[28:31], v[128:131], v[196:199], v[28:31]
	v_mfma_f32_16x16x32_bf16 v[24:27], v[164:167], v[196:199], v[24:27]
	v_mfma_f32_16x16x32_bf16 v[12:15], v[128:131], v[204:207], v[12:15]
	v_mfma_f32_16x16x32_bf16 v[8:11], v[164:167], v[204:207], v[8:11]
	v_mfma_f32_16x16x32_bf16 v[60:63], v[132:135], v[184:187], v[60:63]
	v_mfma_f32_16x16x32_bf16 v[56:59], v[176:179], v[184:187], v[56:59]
	v_mfma_f32_16x16x32_bf16 v[44:47], v[132:135], v[192:195], v[44:47]
	v_mfma_f32_16x16x32_bf16 v[40:43], v[176:179], v[192:195], v[40:43]
	v_mfma_f32_16x16x32_bf16 v[28:31], v[132:135], v[200:203], v[28:31]
	v_mfma_f32_16x16x32_bf16 v[24:27], v[176:179], v[200:203], v[24:27]
	v_mfma_f32_16x16x32_bf16 v[12:15], v[132:135], v[208:211], v[12:15]
	v_mfma_f32_16x16x32_bf16 v[8:11], v[176:179], v[208:211], v[8:11]
	s_setprio 0
	s_barrier
	s_add_u32 s8, s8, 0x40080
	s_addc_u32 s9, s9, 0
	s_add_i32 s10, s10, s48
	v_lshl_add_u64 v[128:129], s[8:9], 0, v[138:139]
	s_mov_b32 m0, s10
	s_nop 0
	global_load_lds_dwordx4 v[128:129], off
	v_lshl_add_u64 v[128:129], s[8:9], 0, v[136:137]
	s_add_i32 m0, s10, 0x2000
	s_nop 0
	global_load_lds_dwordx4 v[128:129], off
	s_waitcnt vmcnt(10)
	s_barrier
	s_setprio 1
	v_mfma_f32_16x16x32_bf16 v[52:55], v[212:215], v[180:183], v[52:55]
	v_mfma_f32_16x16x32_bf16 v[48:51], v[220:223], v[180:183], v[48:51]
	v_mfma_f32_16x16x32_bf16 v[36:39], v[212:215], v[188:191], v[36:39]
	v_mfma_f32_16x16x32_bf16 v[32:35], v[220:223], v[188:191], v[32:35]
	v_mfma_f32_16x16x32_bf16 v[20:23], v[212:215], v[196:199], v[20:23]
	v_mfma_f32_16x16x32_bf16 v[16:19], v[220:223], v[196:199], v[16:19]
	v_mfma_f32_16x16x32_bf16 v[4:7], v[212:215], v[204:207], v[4:7]
	v_mfma_f32_16x16x32_bf16 v[0:3], v[220:223], v[204:207], v[0:3]
	v_mfma_f32_16x16x32_bf16 v[52:55], v[216:219], v[184:187], v[52:55]
	v_mfma_f32_16x16x32_bf16 v[48:51], v[224:227], v[184:187], v[48:51]
	v_mfma_f32_16x16x32_bf16 v[36:39], v[216:219], v[192:195], v[36:39]
	v_mfma_f32_16x16x32_bf16 v[32:35], v[224:227], v[192:195], v[32:35]
	v_mfma_f32_16x16x32_bf16 v[20:23], v[216:219], v[200:203], v[20:23]
	v_mfma_f32_16x16x32_bf16 v[16:19], v[224:227], v[200:203], v[16:19]
	v_mfma_f32_16x16x32_bf16 v[4:7], v[216:219], v[208:211], v[4:7]
	v_mfma_f32_16x16x32_bf16 v[0:3], v[224:227], v[208:211], v[0:3]
	s_setprio 0
	s_add_i32 s38, s38, 2
	s_add_u32 s35, s35, 0x100
	s_addc_u32 s36, s36, 0
	s_add_u32 s6, s6, 0x100
	s_addc_u32 s7, s7, 0
	s_cmp_gt_u32 s38, 13
	s_barrier
	s_cbranch_scc0 .LBB0_412
	v_mbcnt_lo_u32_b32 v237, -1, 0
	v_mbcnt_hi_u32_b32 v237, -1, v237
	v_bfe_i32 v237, v237, 4, 1
	v_and_b32_e32 v238, 24, v237
	v_mov_b32_e32 v239, 0
	s_lshl_b32 s36, s37, 1
	s_add_i32 s6, s36, 0xffffff80
	s_lshr_b32 s63, s6, 4
	s_lshl_b32 s6, s30, 8
	s_add_i32 s63, s63, 4
	s_ashr_i32 s64, s37, 4
	s_or_b32 s23, s6, s55
	s_and_b32 s6, s30, 0xfffffe
	s_cmp_eq_u32 s6, 6
	s_cselect_b64 s[34:35], -1, 0
	s_cmp_eq_u32 s30, 7
	s_cselect_b64 s[30:31], -1, 0
	s_lshl_b32 s6, s37, 8
	s_cmp_lt_i32 s37, 64
	s_movk_i32 s7, 0xf00
	s_cselect_b32 s7, s7, 0x700
	s_cselect_b32 s8, s64, s63
	s_cselect_b32 s25, s60, 0x800
	s_cselect_b32 s65, 12, 11
	s_and_b32 s66, s7, s6
	s_lshl_b32 s7, s8, 11
	s_lshl_b32 s6, s8, 12
	s_addk_i32 s7, 0x2000
	s_cmp_lt_i32 s8, 4
	s_cselect_b32 s6, s6, s7
	s_ashr_i32 s7, s6, 31
	s_lshl_b64 s[6:7], s[6:7], 10
	s_add_u32 s38, s53, s6
	s_addc_u32 s39, s54, s7
	s_ashr_i32 s37, s36, 31
	v_add_u32_e32 v176, s66, v142
	s_lshl_b64 s[40:41], s[36:37], 7
	v_mul_lo_u32 v130, v176, 56
	s_lshr_b32 s67, s25, 1
	v_lshl_add_u64 v[128:129], s[40:41], 0, v[142:143]
	v_ashrrev_i32_e32 v131, 31, v130
	v_lshl_add_u64 v[168:169], v[130:131], 3, s[14:15]
	v_mad_u64_u32 v[164:165], s[8:9], v128, s61, 0
	s_cmpk_gt_i32 s23, 0x1ff
	v_mad_i32_i24 v165, v129, s61, v165
	v_lshl_add_u64 v[128:129], v[168:169], 0, s[18:19]
	s_cselect_b64 s[10:11], -1, 0
	v_cmp_lt_i32_e64 s[6:7], s67, v176
	v_lshl_add_u64 v[166:167], v[128:129], 0, v[140:141]
	s_mov_b64 s[8:9], -1
	s_and_b64 vcc, exec, s[10:11]
	s_cbranch_vccz .LBB0_424
	s_cmpk_gt_u32 s23, 0x109f
	s_cbranch_scc1 .LBB0_423
	s_add_i32 s8, s23, 0xfffffe00
	s_cmpk_gt_u32 s8, 0x1ff
	s_mov_b64 s[42:43], -1
	s_cbranch_scc0 .LBB0_421
	s_add_i32 s9, s23, 0xfffff700
	s_cmpk_lt_u32 s9, 0x400
	s_cselect_b64 s[42:43], -1, 0
	s_or_b64 s[42:43], s[34:35], s[42:43]
	v_mov_b64_e32 v[134:135], v[126:127]
	v_mov_b64_e32 v[130:131], v[122:123]
	s_andn2_b64 vcc, exec, s[42:43]
	v_mov_b64_e32 v[132:133], v[124:125]
	v_mov_b64_e32 v[128:129], v[120:121]
	s_cbranch_vccnz .LBB0_420
	s_andn2_b64 vcc, exec, s[20:21]
	v_mov_b32_e32 v128, v124
	v_mov_b32_e32 v129, v125
	v_mov_b32_e32 v130, v126
	v_mov_b32_e32 v131, v127
	s_cbranch_vccnz .LBB0_419
	v_and_b32_e32 v129, 64, v173
	v_xor_b32_e32 v128, 32, v173
	v_add_u32_e32 v129, 64, v129
	v_cmp_lt_i32_e32 vcc, v128, v129
	v_mov_b32_e32 v129, v141
	s_nop 0
	v_cndmask_b32_e32 v128, v173, v128, vcc
	v_lshlrev_b32_e32 v177, 2, v128
	v_lshlrev_b32_e32 v128, 3, v146
	v_lshl_add_u64 v[132:133], v[168:169], 0, v[128:129]
	s_waitcnt vmcnt(0)
	global_load_dwordx4 v[128:131], v[132:133], off offset:128
	ds_bpermute_b32 v134, v177, v124
	ds_bpermute_b32 v135, v177, v125
	s_waitcnt vmcnt(0) lgkmcnt(0)
	v_mov_b32_e32 v179, v130
	v_mov_b32_e32 v130, v129
	v_mov_b32_e32 v178, v128
	v_pk_mul_f32 v[128:129], v[130:131], v[134:135]
	global_load_dwordx4 v[130:133], v[132:133], off offset:144
	ds_bpermute_b32 v134, v177, v126
	ds_bpermute_b32 v135, v177, v127
	v_cndmask_b32_e64 v129, v129, -v129, s[0:1]
	v_cndmask_b32_e64 v128, v128, -v128, s[0:1]
	v_pk_fma_f32 v[128:129], v[124:125], v[178:179], v[128:129]
	s_waitcnt vmcnt(0) lgkmcnt(0)
	v_mov_b32_e32 v179, v132
	v_mov_b32_e32 v132, v131
	v_mov_b32_e32 v178, v130
	v_pk_mul_f32 v[130:131], v[132:133], v[134:135]
	s_nop 0
	v_cndmask_b32_e64 v131, v131, -v131, s[0:1]
	v_cndmask_b32_e64 v130, v130, -v130, s[0:1]
	v_pk_fma_f32 v[130:131], v[126:127], v[178:179], v[130:131]

.LBB0_1407:
	ds_read_b128 v[128:131], v149
	ds_read_b128 v[132:135], v149 offset:1024
	ds_read_b128 v[164:167], v149 offset:2048
	ds_read_b128 v[176:179], v149 offset:3072
	s_add_u32 s12, s10, 0xfffc0080
	s_addc_u32 s13, s11, -1
	s_cmp_eq_u32 s36, 12
	s_cselect_b32 s15, s25, s13
	s_cselect_b32 s14, s30, s12
	s_cselect_b32 s13, s23, s35
	s_cselect_b32 s12, s31, s34
	v_lshl_add_u64 v[168:169], s[10:11], 0, v[158:159]
	s_add_i32 m0, s49, 0xc000
	ds_read_b128 v[180:183], v171
	ds_read_b128 v[184:187], v171 offset:1024
	ds_read_b128 v[188:191], v171 offset:2048
	ds_read_b128 v[192:195], v171 offset:3072
	ds_read_b128 v[196:199], v171 offset:4096
	ds_read_b128 v[200:203], v171 offset:5120
	ds_read_b128 v[204:207], v171 offset:6144
	ds_read_b128 v[208:211], v171 offset:7168
	global_load_lds_dwordx4 v[168:169], off
	v_lshl_add_u64 v[168:169], s[10:11], 0, v[156:157]
	s_add_i32 m0, s49, 0xe000
	s_nop 0
	global_load_lds_dwordx4 v[168:169], off
	s_waitcnt lgkmcnt(8)
	s_waitcnt vmcnt(10)
	s_barrier
	s_waitcnt lgkmcnt(0)
	s_setprio 1
	s_waitcnt lgkmcnt(0)
	v_mfma_f32_16x16x32_bf16 v[124:127], v[128:131], v[180:183], v[124:127]
	v_mfma_f32_16x16x32_bf16 v[120:123], v[164:167], v[180:183], v[120:123]
	v_mfma_f32_16x16x32_bf16 v[108:111], v[128:131], v[188:191], v[108:111]
	v_mfma_f32_16x16x32_bf16 v[104:107], v[164:167], v[188:191], v[104:107]
	v_mfma_f32_16x16x32_bf16 v[92:95], v[128:131], v[196:199], v[92:95]
	v_mfma_f32_16x16x32_bf16 v[88:91], v[164:167], v[196:199], v[88:91]
	v_mfma_f32_16x16x32_bf16 v[76:79], v[128:131], v[204:207], v[76:79]
	v_mfma_f32_16x16x32_bf16 v[72:75], v[164:167], v[204:207], v[72:75]
	v_mfma_f32_16x16x32_bf16 v[124:127], v[132:135], v[184:187], v[124:127]
	v_mfma_f32_16x16x32_bf16 v[120:123], v[176:179], v[184:187], v[120:123]
	v_mfma_f32_16x16x32_bf16 v[108:111], v[132:135], v[192:195], v[108:111]
	v_mfma_f32_16x16x32_bf16 v[104:107], v[176:179], v[192:195], v[104:107]
	v_mfma_f32_16x16x32_bf16 v[92:95], v[132:135], v[200:203], v[92:95]
	v_mfma_f32_16x16x32_bf16 v[88:91], v[176:179], v[200:203], v[88:91]
	v_mfma_f32_16x16x32_bf16 v[76:79], v[132:135], v[208:211], v[76:79]
	v_mfma_f32_16x16x32_bf16 v[72:75], v[176:179], v[208:211], v[72:75]
	s_setprio 0
	s_barrier
	s_add_i32 s37, s58, s48
	v_lshl_add_u64 v[168:169], s[12:13], 0, v[138:139]
	s_mov_b32 m0, s37
	ds_read_b128 v[212:215], v172
	ds_read_b128 v[216:219], v172 offset:1024
	ds_read_b128 v[220:223], v172 offset:2048
	ds_read_b128 v[224:227], v172 offset:3072
	global_load_lds_dwordx4 v[168:169], off
	v_lshl_add_u64 v[228:229], s[12:13], 0, v[136:137]
	s_add_i32 m0, s37, 0x2000
	s_nop 0
	global_load_lds_dwordx4 v[228:229], off
	s_waitcnt vmcnt(10)
	s_barrier
	s_waitcnt lgkmcnt(0)
	s_setprio 1
	s_waitcnt lgkmcnt(0)
	v_mfma_f32_16x16x32_bf16 v[116:119], v[212:215], v[180:183], v[116:119]
	v_mfma_f32_16x16x32_bf16 v[112:115], v[220:223], v[180:183], v[112:115]
	v_mfma_f32_16x16x32_bf16 v[100:103], v[212:215], v[188:191], v[100:103]
	v_mfma_f32_16x16x32_bf16 v[96:99], v[220:223], v[188:191], v[96:99]
	v_mfma_f32_16x16x32_bf16 v[84:87], v[212:215], v[196:199], v[84:87]
	v_mfma_f32_16x16x32_bf16 v[80:83], v[220:223], v[196:199], v[80:83]
	v_mfma_f32_16x16x32_bf16 v[68:71], v[212:215], v[204:207], v[68:71]
	v_mfma_f32_16x16x32_bf16 v[64:67], v[220:223], v[204:207], v[64:67]
	v_mfma_f32_16x16x32_bf16 v[116:119], v[216:219], v[184:187], v[116:119]
	v_mfma_f32_16x16x32_bf16 v[112:115], v[224:227], v[184:187], v[112:115]
	v_mfma_f32_16x16x32_bf16 v[100:103], v[216:219], v[192:195], v[100:103]
	v_mfma_f32_16x16x32_bf16 v[96:99], v[224:227], v[192:195], v[96:99]
	v_mfma_f32_16x16x32_bf16 v[84:87], v[216:219], v[200:203], v[84:87]
	v_mfma_f32_16x16x32_bf16 v[80:83], v[224:227], v[200:203], v[80:83]
	v_mfma_f32_16x16x32_bf16 v[68:71], v[216:219], v[208:211], v[68:71]
	v_mfma_f32_16x16x32_bf16 v[64:67], v[224:227], v[208:211], v[64:67]
	s_setprio 0
	s_mov_b32 m0, s49
	v_lshl_add_u64 v[230:231], s[14:15], 0, v[138:139]
	s_barrier
	ds_read_b128 v[180:183], v171 offset:16384
	ds_read_b128 v[184:187], v171 offset:17408
	ds_read_b128 v[188:191], v171 offset:18432
	ds_read_b128 v[192:195], v171 offset:19456
	ds_read_b128 v[196:199], v171 offset:20480
	ds_read_b128 v[200:203], v171 offset:21504
	ds_read_b128 v[204:207], v171 offset:22528
	ds_read_b128 v[208:211], v171 offset:23552
	global_load_lds_dwordx4 v[230:231], off
	v_lshl_add_u64 v[232:233], s[14:15], 0, v[136:137]
	s_mov_b32 m0, s50
	s_nop 0
	global_load_lds_dwordx4 v[232:233], off
	s_barrier
	s_waitcnt lgkmcnt(0)
	s_setprio 1
	s_waitcnt lgkmcnt(0)
	v_mfma_f32_16x16x32_bf16 v[60:63], v[128:131], v[180:183], v[60:63]
	v_mfma_f32_16x16x32_bf16 v[56:59], v[164:167], v[180:183], v[56:59]
	v_mfma_f32_16x16x32_bf16 v[44:47], v[128:131], v[188:191], v[44:47]
	v_mfma_f32_16x16x32_bf16 v[40:43], v[164:167], v[188:191], v[40:43]
	v_mfma_f32_16x16x32_bf16 v[28:31], v[128:131], v[196:199], v[28:31]
	v_mfma_f32_16x16x32_bf16 v[24:27], v[164:167], v[196:199], v[24:27]
	v_mfma_f32_16x16x32_bf16 v[12:15], v[128:131], v[204:207], v[12:15]
	v_mfma_f32_16x16x32_bf16 v[8:11], v[164:167], v[204:207], v[8:11]
	v_mfma_f32_16x16x32_bf16 v[60:63], v[132:135], v[184:187], v[60:63]
	v_mfma_f32_16x16x32_bf16 v[56:59], v[176:179], v[184:187], v[56:59]
	v_mfma_f32_16x16x32_bf16 v[44:47], v[132:135], v[192:195], v[44:47]
	v_mfma_f32_16x16x32_bf16 v[40:43], v[176:179], v[192:195], v[40:43]
	v_mfma_f32_16x16x32_bf16 v[28:31], v[132:135], v[200:203], v[28:31]
	v_mfma_f32_16x16x32_bf16 v[24:27], v[176:179], v[200:203], v[24:27]
	v_mfma_f32_16x16x32_bf16 v[12:15], v[132:135], v[208:211], v[12:15]
	v_mfma_f32_16x16x32_bf16 v[8:11], v[176:179], v[208:211], v[8:11]
	s_setprio 0
	s_barrier
	s_add_u32 s38, s12, 0x40000
	s_addc_u32 s39, s13, 0
	s_add_i32 s37, s59, s48
	v_lshl_add_u64 v[128:129], s[38:39], 0, v[138:139]
	s_mov_b32 m0, s37
	s_nop 0
	global_load_lds_dwordx4 v[128:129], off
	v_lshl_add_u64 v[128:129], s[38:39], 0, v[136:137]
	s_add_i32 m0, s37, 0x2000
	s_nop 0
	global_load_lds_dwordx4 v[128:129], off
	s_waitcnt vmcnt(10)
	s_barrier
	s_setprio 1
	v_mfma_f32_16x16x32_bf16 v[52:55], v[212:215], v[180:183], v[52:55]
	v_mfma_f32_16x16x32_bf16 v[48:51], v[220:223], v[180:183], v[48:51]
	v_mfma_f32_16x16x32_bf16 v[36:39], v[212:215], v[188:191], v[36:39]
	v_mfma_f32_16x16x32_bf16 v[32:35], v[220:223], v[188:191], v[32:35]
	v_mfma_f32_16x16x32_bf16 v[20:23], v[212:215], v[196:199], v[20:23]
	v_mfma_f32_16x16x32_bf16 v[16:19], v[220:223], v[196:199], v[16:19]
	v_mfma_f32_16x16x32_bf16 v[4:7], v[212:215], v[204:207], v[4:7]
	v_mfma_f32_16x16x32_bf16 v[0:3], v[220:223], v[204:207], v[0:3]
	v_mfma_f32_16x16x32_bf16 v[52:55], v[216:219], v[184:187], v[52:55]
	v_mfma_f32_16x16x32_bf16 v[48:51], v[224:227], v[184:187], v[48:51]
	v_mfma_f32_16x16x32_bf16 v[36:39], v[216:219], v[192:195], v[36:39]
	v_mfma_f32_16x16x32_bf16 v[32:35], v[224:227], v[192:195], v[32:35]
	v_mfma_f32_16x16x32_bf16 v[20:23], v[216:219], v[200:203], v[20:23]
	v_mfma_f32_16x16x32_bf16 v[16:19], v[224:227], v[200:203], v[16:19]
	v_mfma_f32_16x16x32_bf16 v[4:7], v[216:219], v[208:211], v[4:7]
	v_mfma_f32_16x16x32_bf16 v[0:3], v[224:227], v[208:211], v[0:3]
	s_setprio 0
	s_add_i32 s37, 0, 0x18000
	v_add_u32_e32 v175, s37, v147
	s_barrier
	ds_read_b128 v[128:131], v175
	ds_read_b128 v[132:135], v175 offset:1024
	ds_read_b128 v[164:167], v175 offset:2048
	ds_read_b128 v[176:179], v175 offset:3072
	s_add_u32 s14, s14, 0x40000
	s_addc_u32 s15, s15, 0
	s_mov_b32 m0, s51
	v_lshl_add_u64 v[212:213], s[14:15], 0, v[138:139]
	ds_read_b128 v[180:183], v171 offset:32768
	ds_read_b128 v[184:187], v171 offset:33792
	ds_read_b128 v[188:191], v171 offset:34816
	ds_read_b128 v[192:195], v171 offset:35840
	ds_read_b128 v[196:199], v171 offset:36864
	ds_read_b128 v[200:203], v171 offset:37888
	ds_read_b128 v[204:207], v171 offset:38912
	ds_read_b128 v[208:211], v171 offset:39936
	global_load_lds_dwordx4 v[212:213], off
	v_lshl_add_u64 v[212:213], s[14:15], 0, v[136:137]
	s_mov_b32 m0, s52
	s_nop 0
	global_load_lds_dwordx4 v[212:213], off
	s_waitcnt lgkmcnt(8)
	s_waitcnt vmcnt(10)
	s_barrier
	s_waitcnt lgkmcnt(0)
	s_setprio 1
	s_waitcnt lgkmcnt(0)
	v_mfma_f32_16x16x32_bf16 v[124:127], v[128:131], v[180:183], v[124:127]
	v_mfma_f32_16x16x32_bf16 v[120:123], v[164:167], v[180:183], v[120:123]
	v_mfma_f32_16x16x32_bf16 v[108:111], v[128:131], v[188:191], v[108:111]
	v_mfma_f32_16x16x32_bf16 v[104:107], v[164:167], v[188:191], v[104:107]
	v_mfma_f32_16x16x32_bf16 v[92:95], v[128:131], v[196:199], v[92:95]
	v_mfma_f32_16x16x32_bf16 v[88:91], v[164:167], v[196:199], v[88:91]
	v_mfma_f32_16x16x32_bf16 v[76:79], v[128:131], v[204:207], v[76:79]
	v_mfma_f32_16x16x32_bf16 v[72:75], v[164:167], v[204:207], v[72:75]
	v_mfma_f32_16x16x32_bf16 v[124:127], v[132:135], v[184:187], v[124:127]
	v_mfma_f32_16x16x32_bf16 v[120:123], v[176:179], v[184:187], v[120:123]
	v_mfma_f32_16x16x32_bf16 v[108:111], v[132:135], v[192:195], v[108:111]
	v_mfma_f32_16x16x32_bf16 v[104:107], v[176:179], v[192:195], v[104:107]
	v_mfma_f32_16x16x32_bf16 v[92:95], v[132:135], v[200:203], v[92:95]
	v_mfma_f32_16x16x32_bf16 v[88:91], v[176:179], v[200:203], v[88:91]
	v_mfma_f32_16x16x32_bf16 v[76:79], v[132:135], v[208:211], v[76:79]
	v_mfma_f32_16x16x32_bf16 v[72:75], v[176:179], v[208:211], v[72:75]
	s_setprio 0
	s_barrier
	s_add_i32 s14, 0, 0x1c000
	s_add_i32 s15, s37, s48
	v_add_u32_e32 v175, s14, v147
	v_lshl_add_u64 v[168:169], v[168:169], 0, s[18:19]
	s_mov_b32 m0, s15
	ds_read_b128 v[212:215], v175
	ds_read_b128 v[216:219], v175 offset:1024
	ds_read_b128 v[220:223], v175 offset:2048
	ds_read_b128 v[224:227], v175 offset:3072
	global_load_lds_dwordx4 v[168:169], off
	v_lshl_add_u64 v[168:169], v[228:229], 0, s[18:19]
	s_add_i32 m0, s15, 0x2000
	s_nop 0
	global_load_lds_dwordx4 v[168:169], off
	s_waitcnt vmcnt(10)
	s_barrier
	s_waitcnt lgkmcnt(0)
	s_setprio 1
	s_waitcnt lgkmcnt(0)
	v_mfma_f32_16x16x32_bf16 v[116:119], v[212:215], v[180:183], v[116:119]
	v_mfma_f32_16x16x32_bf16 v[112:115], v[220:223], v[180:183], v[112:115]
	v_mfma_f32_16x16x32_bf16 v[100:103], v[212:215], v[188:191], v[100:103]
	v_mfma_f32_16x16x32_bf16 v[96:99], v[220:223], v[188:191], v[96:99]
	v_mfma_f32_16x16x32_bf16 v[84:87], v[212:215], v[196:199], v[84:87]
	v_mfma_f32_16x16x32_bf16 v[80:83], v[220:223], v[196:199], v[80:83]
	v_mfma_f32_16x16x32_bf16 v[68:71], v[212:215], v[204:207], v[68:71]
	v_mfma_f32_16x16x32_bf16 v[64:67], v[220:223], v[204:207], v[64:67]
	v_mfma_f32_16x16x32_bf16 v[116:119], v[216:219], v[184:187], v[116:119]
	v_mfma_f32_16x16x32_bf16 v[112:115], v[224:227], v[184:187], v[112:115]
	v_mfma_f32_16x16x32_bf16 v[100:103], v[216:219], v[192:195], v[100:103]
	v_mfma_f32_16x16x32_bf16 v[96:99], v[224:227], v[192:195], v[96:99]
	v_mfma_f32_16x16x32_bf16 v[84:87], v[216:219], v[200:203], v[84:87]
	v_mfma_f32_16x16x32_bf16 v[80:83], v[224:227], v[200:203], v[80:83]
	v_mfma_f32_16x16x32_bf16 v[68:71], v[216:219], v[208:211], v[68:71]
	v_mfma_f32_16x16x32_bf16 v[64:67], v[224:227], v[208:211], v[64:67]
	s_setprio 0
	s_mov_b32 m0, s56
	v_lshl_add_u64 v[168:169], v[230:231], 0, s[18:19]
	s_barrier
	ds_read_b128 v[180:183], v171 offset:49152
	ds_read_b128 v[184:187], v171 offset:50176
	ds_read_b128 v[188:191], v171 offset:51200
	ds_read_b128 v[192:195], v171 offset:52224
	ds_read_b128 v[196:199], v171 offset:53248
	ds_read_b128 v[200:203], v171 offset:54272
	ds_read_b128 v[204:207], v171 offset:55296
	ds_read_b128 v[208:211], v171 offset:56320
	global_load_lds_dwordx4 v[168:169], off
	v_lshl_add_u64 v[168:169], v[232:233], 0, s[18:19]
	s_mov_b32 m0, s57
	s_nop 0
	global_load_lds_dwordx4 v[168:169], off
	s_barrier
	s_waitcnt lgkmcnt(0)
	s_setprio 1
	s_waitcnt lgkmcnt(0)
	v_mfma_f32_16x16x32_bf16 v[60:63], v[128:131], v[180:183], v[60:63]
	v_mfma_f32_16x16x32_bf16 v[56:59], v[164:167], v[180:183], v[56:59]
	v_mfma_f32_16x16x32_bf16 v[44:47], v[128:131], v[188:191], v[44:47]
	v_mfma_f32_16x16x32_bf16 v[40:43], v[164:167], v[188:191], v[40:43]
	v_mfma_f32_16x16x32_bf16 v[28:31], v[128:131], v[196:199], v[28:31]
	v_mfma_f32_16x16x32_bf16 v[24:27], v[164:167], v[196:199], v[24:27]
	v_mfma_f32_16x16x32_bf16 v[12:15], v[128:131], v[204:207], v[12:15]
	v_mfma_f32_16x16x32_bf16 v[8:11], v[164:167], v[204:207], v[8:11]
	v_mfma_f32_16x16x32_bf16 v[60:63], v[132:135], v[184:187], v[60:63]
	v_mfma_f32_16x16x32_bf16 v[56:59], v[176:179], v[184:187], v[56:59]
	v_mfma_f32_16x16x32_bf16 v[44:47], v[132:135], v[192:195], v[44:47]
	v_mfma_f32_16x16x32_bf16 v[40:43], v[176:179], v[192:195], v[40:43]
	v_mfma_f32_16x16x32_bf16 v[28:31], v[132:135], v[200:203], v[28:31]
	v_mfma_f32_16x16x32_bf16 v[24:27], v[176:179], v[200:203], v[24:27]
	v_mfma_f32_16x16x32_bf16 v[12:15], v[132:135], v[208:211], v[12:15]
	v_mfma_f32_16x16x32_bf16 v[8:11], v[176:179], v[208:211], v[8:11]
	s_setprio 0
	s_barrier
	s_add_u32 s12, s12, 0x40080
	s_addc_u32 s13, s13, 0
	s_add_i32 s14, s14, s48
	v_lshl_add_u64 v[128:129], s[12:13], 0, v[138:139]
	s_mov_b32 m0, s14
	s_nop 0
	global_load_lds_dwordx4 v[128:129], off
	v_lshl_add_u64 v[128:129], s[12:13], 0, v[136:137]
	s_add_i32 m0, s14, 0x2000
	s_nop 0
	global_load_lds_dwordx4 v[128:129], off
	s_waitcnt vmcnt(10)
	s_barrier
	s_setprio 1
	v_mfma_f32_16x16x32_bf16 v[52:55], v[212:215], v[180:183], v[52:55]
	v_mfma_f32_16x16x32_bf16 v[48:51], v[220:223], v[180:183], v[48:51]
	v_mfma_f32_16x16x32_bf16 v[36:39], v[212:215], v[188:191], v[36:39]
	v_mfma_f32_16x16x32_bf16 v[32:35], v[220:223], v[188:191], v[32:35]
	v_mfma_f32_16x16x32_bf16 v[20:23], v[212:215], v[196:199], v[20:23]
	v_mfma_f32_16x16x32_bf16 v[16:19], v[220:223], v[196:199], v[16:19]
	v_mfma_f32_16x16x32_bf16 v[4:7], v[212:215], v[204:207], v[4:7]
	v_mfma_f32_16x16x32_bf16 v[0:3], v[220:223], v[204:207], v[0:3]
	v_mfma_f32_16x16x32_bf16 v[52:55], v[216:219], v[184:187], v[52:55]
	v_mfma_f32_16x16x32_bf16 v[48:51], v[224:227], v[184:187], v[48:51]
	v_mfma_f32_16x16x32_bf16 v[36:39], v[216:219], v[192:195], v[36:39]
	v_mfma_f32_16x16x32_bf16 v[32:35], v[224:227], v[192:195], v[32:35]
	v_mfma_f32_16x16x32_bf16 v[20:23], v[216:219], v[200:203], v[20:23]
	v_mfma_f32_16x16x32_bf16 v[16:19], v[224:227], v[200:203], v[16:19]
	v_mfma_f32_16x16x32_bf16 v[4:7], v[216:219], v[208:211], v[4:7]
	v_mfma_f32_16x16x32_bf16 v[0:3], v[224:227], v[208:211], v[0:3]
	s_setprio 0
	s_add_i32 s36, s36, 2
	s_add_u32 s34, s34, 0x100
	s_addc_u32 s35, s35, 0
	s_add_u32 s10, s10, 0x100
	s_addc_u32 s11, s11, 0
	s_cmp_gt_u32 s36, 13
	s_barrier
	s_cbranch_scc0 .LBB0_1407
	v_mbcnt_lo_u32_b32 v237, -1, 0
	v_mbcnt_hi_u32_b32 v237, -1, v237
	v_bfe_i32 v237, v237, 4, 1
	v_and_b32_e32 v238, 24, v237
	v_mov_b32_e32 v239, 0
	s_lshl_b32 s36, s42, 1
	s_add_i32 s10, s36, 0xffffff80
	s_lshr_b32 s63, s10, 4
	s_lshl_b32 s10, s40, 8
	s_add_i32 s63, s63, 4
	s_ashr_i32 s64, s42, 4
	s_or_b32 s23, s10, s55
	s_and_b32 s10, s40, 0xfffffe
	s_cmp_eq_u32 s10, 6
	s_cselect_b64 s[34:35], -1, 0
	s_cmp_eq_u32 s40, 7
	s_cselect_b64 s[30:31], -1, 0
	s_lshl_b32 s10, s42, 8
	s_cmp_lt_i32 s42, 64
	s_movk_i32 s11, 0xf00
	s_cselect_b32 s11, s11, 0x700
	s_cselect_b32 s12, s64, s63
	s_cselect_b32 s25, s60, 0x800
	s_cselect_b32 s65, 12, 11
	s_and_b32 s66, s11, s10
	s_lshl_b32 s11, s12, 11
	s_lshl_b32 s10, s12, 12
	s_addk_i32 s11, 0x2000
	s_cmp_lt_i32 s12, 4
	s_cselect_b32 s10, s10, s11
	s_ashr_i32 s11, s10, 31
	s_lshl_b64 s[10:11], s[10:11], 10
	s_add_u32 s38, s53, s10
	s_addc_u32 s39, s54, s11
	s_ashr_i32 s37, s36, 31
	v_add_u32_e32 v175, s66, v142
	s_lshl_b64 s[40:41], s[36:37], 7
	v_mul_lo_u32 v130, v175, 56
	s_lshr_b32 s67, s25, 1
	v_lshl_add_u64 v[128:129], s[40:41], 0, v[142:143]
	v_ashrrev_i32_e32 v131, 31, v130
	v_lshl_add_u64 v[168:169], v[130:131], 3, s[16:17]
	v_mad_u64_u32 v[164:165], s[12:13], v128, s61, 0
	s_cmpk_gt_i32 s23, 0x1ff
	v_mad_i32_i24 v165, v129, s61, v165
	v_lshl_add_u64 v[128:129], v[168:169], 0, s[2:3]
	s_cselect_b64 s[14:15], -1, 0
	v_cmp_lt_i32_e64 s[10:11], s67, v175
	v_lshl_add_u64 v[166:167], v[128:129], 0, v[140:141]
	s_mov_b64 s[12:13], -1
	s_and_b64 vcc, exec, s[14:15]
	s_cbranch_vccz .LBB0_1419
	s_cmpk_gt_u32 s23, 0x109f
	s_cbranch_scc1 .LBB0_1418
	s_add_i32 s12, s23, 0xfffffe00
	s_cmpk_gt_u32 s12, 0x1ff
	s_mov_b64 s[42:43], -1
	s_cbranch_scc0 .LBB0_1416
	s_add_i32 s13, s23, 0xfffff700
	s_cmpk_lt_u32 s13, 0x400
	s_cselect_b64 s[42:43], -1, 0
	s_or_b64 s[42:43], s[34:35], s[42:43]
	v_mov_b64_e32 v[134:135], v[126:127]
	v_mov_b64_e32 v[130:131], v[122:123]
	s_andn2_b64 vcc, exec, s[42:43]
	v_mov_b64_e32 v[132:133], v[124:125]
	v_mov_b64_e32 v[128:129], v[120:121]
	s_cbranch_vccnz .LBB0_1415
	s_andn2_b64 vcc, exec, s[20:21]
	v_mov_b32_e32 v128, v124
	v_mov_b32_e32 v129, v125
	v_mov_b32_e32 v130, v126
	v_mov_b32_e32 v131, v127
	s_cbranch_vccnz .LBB0_1414
	v_and_b32_e32 v129, 64, v170
	v_xor_b32_e32 v128, 32, v170
	v_add_u32_e32 v129, 64, v129
	v_cmp_lt_i32_e32 vcc, v128, v129
	v_mov_b32_e32 v129, v141
	s_nop 0
	v_cndmask_b32_e32 v128, v170, v128, vcc
	v_lshlrev_b32_e32 v178, 2, v128
	v_lshlrev_b32_e32 v128, 3, v146
	v_lshl_add_u64 v[132:133], v[168:169], 0, v[128:129]
	s_waitcnt vmcnt(0)
	global_load_dwordx4 v[128:131], v[132:133], off offset:128
	ds_bpermute_b32 v134, v178, v124
	ds_bpermute_b32 v135, v178, v125
	s_waitcnt vmcnt(0) lgkmcnt(0)
	v_mov_b32_e32 v177, v130
	v_mov_b32_e32 v130, v129
	v_mov_b32_e32 v176, v128
	v_pk_mul_f32 v[128:129], v[130:131], v[134:135]
	global_load_dwordx4 v[130:133], v[132:133], off offset:144
	ds_bpermute_b32 v134, v178, v126
	ds_bpermute_b32 v135, v178, v127
	v_cndmask_b32_e64 v129, v129, -v129, s[6:7]
	v_cndmask_b32_e64 v128, v128, -v128, s[6:7]
	v_pk_fma_f32 v[128:129], v[124:125], v[176:177], v[128:129]
	s_waitcnt vmcnt(0) lgkmcnt(0)
	v_mov_b32_e32 v177, v132
	v_mov_b32_e32 v132, v131
	v_mov_b32_e32 v176, v130
	v_pk_mul_f32 v[130:131], v[132:133], v[134:135]
	s_nop 0
	v_cndmask_b32_e64 v131, v131, -v131, s[6:7]
	v_cndmask_b32_e64 v130, v130, -v130, s[6:7]
	v_pk_fma_f32 v[130:131], v[126:127], v[176:177], v[130:131]
